# PEER value pass: four fp4 activation terms as four rows of one scaled-MFMA A operand (per-lane block scale) + f32 row adds, 16 MFMAs instead of 64 dependent ones per token slice; same fp4 operands and
# speedup vs baseline: 1.1054x; 1.0244x over previous
.LBB0_1111:
	s_or_b64 exec, exec, s[42:43]
	s_mul_i32 s3, s54, 0x36000
	s_mul_hi_u32 s2, s54, 0x36000
	s_add_u32 s3, s58, s3
	s_addc_u32 s2, s59, s2
	s_add_u32 s38, s3, 0x13405000
	s_addc_u32 s39, s2, 0
	s_add_u32 s54, s58, 0x13600000
	s_addc_u32 s55, s59, 0
	s_add_u32 s2, s58, s50
	v_lshlrev_b32_e32 v2, 4, v0
	s_addc_u32 s3, s59, s51
	v_and_b32_e32 v128, 0x70, v2
	v_lshl_add_u64 v[2:3], s[2:3], 0, v[128:129]
	s_mov_b64 s[2:3], 0xac00000
	v_ashrrev_i32_e32 v89, 31, v88
	v_and_b32_e32 v10, 63, v0
	v_lshl_add_u64 v[90:91], v[2:3], 0, s[2:3]
	v_lshlrev_b64 v[2:3], 9, v[88:89]
	s_waitcnt vmcnt(0)
	v_lshl_add_u64 v[4:5], s[52:53], 0, v[2:3]
	v_lshlrev_b32_e32 v6, 2, v10
	v_mov_b32_e32 v7, v129
	v_lshl_add_u64 v[2:3], s[64:65], 0, v[2:3]
	v_lshl_add_u64 v[94:95], v[2:3], 0, v[6:7]
	v_lshlrev_b64 v[2:3], 11, v[88:89]
	v_lshl_add_u64 v[92:93], v[4:5], 0, v[6:7]
	v_lshl_add_u64 v[2:3], s[54:55], 0, v[2:3]
	v_lshlrev_b32_e32 v4, 3, v10
	v_mov_b32_e32 v5, v129
	v_lshl_add_u64 v[96:97], v[2:3], 0, v[4:5]
	v_add_u32_e32 v2, 0xffffe000, v88
	v_lshrrev_b32_e32 v2, 12, v2
	v_add_u32_e32 v2, 1, v2
	v_cmp_lt_i32_e64 s[42:43], s22, v88
	v_mov_b32_e32 v9, v129
	s_movk_i32 s30, 0x4800
	v_cndmask_b32_e64 v8, 0, v2, s[42:43]
	v_mov_b64_e32 v[2:3], s[38:39]
	v_mad_u64_u32 v[2:3], s[42:43], v8, s23, v[2:3]
	v_lshlrev_b32_e32 v8, 4, v10
	v_lshl_add_u64 v[98:99], v[2:3], 0, v[8:9]
	v_lshlrev_b32_e32 v2, 1, v0
	v_lshl_add_u64 v[100:101], s[54:55], 0, v[4:5]
	v_and_b32_e32 v2, 0x60, v2
	v_lshlrev_b32_e32 v4, 5, v0
	v_and_b32_e32 v12, 15, v0
	v_mul_lo_u32 v1, v1, s30
	v_lshlrev_b32_e32 v3, 2, v2
	v_and_b32_e32 v4, 0x60, v4
	v_bfe_u32 v11, v0, 3, 3
	v_or3_b32 v124, v1, v3, v4
	v_and_b32_e32 v3, 12, v0
	v_and_b32_e32 v0, 48, v0
	v_or_b32_e32 v2, v2, v12
	v_or_b32_e32 v122, v1, v6
	v_cmp_eq_u32_e64 s[48:49], 12, v3
	v_lshl_or_b32 v125, v0, 2, v1
	v_and_b32_e32 v234, 3, v133
	v_lshlrev_b32_e32 v233, 1, v234
	v_sub_u32_e32 v233, 0x7f, v233
	v_lshl_add_u32 v234, v234, 4, v125
	v_or_b32_e32 v0, v1, v128
	v_mul_u32_u24_e32 v2, 0x88, v2
	v_mul_u32_u24_e32 v3, 12, v10
	v_mul_u32_u24_e32 v4, 0x88, v11
	s_mov_b32 s2, 0
	v_cmp_ne_u32_e32 vcc, 0, v109
	v_lshl_add_u64 v[102:103], s[38:39], 0, v[8:9]
	v_cmp_lt_i32_e64 s[42:43], 0, v109
	v_lshl_or_b32 v123, v11, 2, v1
	v_cmp_lt_u32_e64 s[44:45], 3, v12
	v_cmp_lt_u32_e64 s[46:47], 7, v12
	v_cmp_gt_u32_e64 s[50:51], 16, v10
	v_lshl_add_u64 v[104:105], s[52:53], 0, v[6:7]
	v_lshl_add_u64 v[106:107], s[64:65], 0, v[6:7]
	v_add_u32_e32 v126, v0, v4
	v_add_u32_e32 v127, v1, v2
	v_add_u32_e32 v128, v122, v3
	s_branch .LBB0_1113

.LBB0_1123:
	s_or_b64 exec, exec, s[52:53]
	ds_write_b32 v122, v80 offset:17408
	ds_read_b128 v[84:87], v234 offset:17408
	s_waitcnt vmcnt(16)
	ds_write2_b64 v126, v[144:145], v[146:147] offset1:1
	s_waitcnt vmcnt(15)
	ds_write2_b64 v126, v[148:149], v[150:151] offset0:136 offset1:137
	s_waitcnt vmcnt(14)
	v_add_u32_e32 v8, 0x880, v126
	ds_write2_b64 v8, v[152:153], v[154:155] offset1:1
	s_waitcnt vmcnt(13)
	v_add_u32_e32 v8, 0xcc0, v126
	ds_write2_b64 v8, v[156:157], v[158:159] offset1:1
	s_waitcnt vmcnt(12)
	v_add_u32_e32 v8, 0x1100, v126
	ds_write2_b64 v8, v[160:161], v[162:163] offset1:1
	s_waitcnt vmcnt(11)
	v_add_u32_e32 v8, 0x1540, v126
	ds_write2_b64 v8, v[164:165], v[166:167] offset1:1
	s_waitcnt vmcnt(10)
	v_add_u32_e32 v8, 0x1980, v126
	ds_write2_b64 v8, v[168:169], v[170:171] offset1:1
	s_waitcnt vmcnt(9)
	v_add_u32_e32 v8, 0x1dc0, v126
	ds_write2_b64 v8, v[172:173], v[174:175] offset1:1
	s_waitcnt vmcnt(8)
	v_add_u32_e32 v8, 0x2200, v126
	ds_write2_b64 v8, v[192:193], v[194:195] offset1:1
	s_waitcnt vmcnt(7)
	v_add_u32_e32 v8, 0x2640, v126
	ds_write2_b64 v8, v[196:197], v[198:199] offset1:1
	s_waitcnt vmcnt(6)
	v_add_u32_e32 v8, 0x2a80, v126
	ds_write2_b64 v8, v[200:201], v[202:203] offset1:1
	s_waitcnt vmcnt(5)
	v_add_u32_e32 v8, 0x2ec0, v126
	ds_write2_b64 v8, v[204:205], v[206:207] offset1:1
	s_waitcnt vmcnt(4)
	v_add_u32_e32 v8, 0x3300, v126
	ds_write2_b64 v8, v[208:209], v[210:211] offset1:1
	s_waitcnt vmcnt(3)
	v_add_u32_e32 v8, 0x3740, v126
	ds_write2_b64 v8, v[212:213], v[214:215] offset1:1
	s_waitcnt vmcnt(2)
	v_add_u32_e32 v8, 0x3b80, v126
	ds_write2_b64 v8, v[216:217], v[218:219] offset1:1
	s_waitcnt vmcnt(1)
	v_add_u32_e32 v8, 0x3fc0, v126
	ds_write2_b64 v8, v[220:221], v[222:223] offset1:1
	v_cmp_lt_i32_e64 s[74:75], s3, v109
	s_add_i32 s30, s3, 1
	v_cmp_lt_i32_e64 s[78:79], s30, v109
	s_and_saveexec_b64 s[72:73], s[74:75]
	s_cbranch_execz .Lgv_mid_end
	ds_write2st64_b32 v122, v130, v131 offset0:68 offset1:69
	v_add_u32_e32 v56, s84, v120
	v_ashrrev_i32_e32 v57, 31, v56
	v_lshlrev_b64 v[58:59], 9, v[56:57]
	v_lshl_add_u64 v[60:61], v[106:107], 0, v[58:59]
	global_load_dword v89, v[60:61], off sc1
	global_load_dword v108, v[60:61], off offset:256 sc1
	v_lshlrev_b64 v[58:59], 11, v[56:57]
	v_lshl_add_u64 v[58:59], v[110:111], 0, v[58:59]
	global_load_dwordx2 v[142:143], v[58:59], off
	s_and_saveexec_b64 s[38:39], s[78:79]
	s_cbranch_execz .Lgv_mid_noidx
	v_add_u32_e32 v58, s84, v56
	v_ashrrev_i32_e32 v59, 31, v58
	v_lshlrev_b64 v[58:59], 9, v[58:59]
	v_lshl_add_u64 v[58:59], v[104:105], 0, v[58:59]
	global_load_dword v130, v[58:59], off
	global_load_dword v131, v[58:59], off offset:256

.Lgv_mid_end:
	s_or_b64 exec, exec, s[72:73]
	ds_read_b64_tr_b4 v[68:69], v127
	ds_read_b64_tr_b4 v[64:65], v127 offset:8
	ds_read_b64_tr_b4 v[60:61], v127 offset:16
	ds_read_b64_tr_b4 v[56:57], v127 offset:24
	ds_read_b64_tr_b4 v[52:53], v127 offset:32
	ds_read_b64_tr_b4 v[48:49], v127 offset:40
	ds_read_b64_tr_b4 v[44:45], v127 offset:48
	ds_read_b64_tr_b4 v[36:37], v127 offset:56
	ds_read_b64_tr_b4 v[70:71], v127 offset:2176
	ds_read_b64_tr_b4 v[66:67], v127 offset:2184
	ds_read_b64_tr_b4 v[62:63], v127 offset:2192
	ds_read_b64_tr_b4 v[58:59], v127 offset:2200
	ds_read_b64_tr_b4 v[54:55], v127 offset:2208
	ds_read_b64_tr_b4 v[50:51], v127 offset:2216
	ds_read_b64_tr_b4 v[46:47], v127 offset:2224
	ds_read_b64_tr_b4 v[38:39], v127 offset:2232
	ds_read_b64_tr_b4 v[40:41], v127 offset:64
	ds_read_b64_tr_b4 v[32:33], v127 offset:72
	ds_read_b64_tr_b4 v[28:29], v127 offset:80
	ds_read_b64_tr_b4 v[24:25], v127 offset:88
	ds_read_b64_tr_b4 v[42:43], v127 offset:2240
	ds_read_b64_tr_b4 v[34:35], v127 offset:2248
	ds_read_b64_tr_b4 v[30:31], v127 offset:2256
	ds_read_b64_tr_b4 v[26:27], v127 offset:2264
	ds_read_b64_tr_b4 v[20:21], v127 offset:96
	ds_read_b64_tr_b4 v[16:17], v127 offset:104
	ds_read_b64_tr_b4 v[12:13], v127 offset:112
	ds_read_b64_tr_b4 v[8:9], v127 offset:120
	ds_read_b64_tr_b4 v[22:23], v127 offset:2272
	ds_read_b64_tr_b4 v[18:19], v127 offset:2280
	ds_read_b64_tr_b4 v[14:15], v127 offset:2288
	ds_read_b64_tr_b4 v[10:11], v127 offset:2296
	s_and_saveexec_b64 s[52:53], s[50:51]
	s_cbranch_execz .LBB0_1116
	s_waitcnt lgkmcnt(0)
	v_mfma_scale_f32_16x16x128_f8f6f4 v[68:71], v[84:87], v[68:71], 0, v233, v183 op_sel_hi:[0,0,0] cbsz:4 blgp:4
	v_mfma_scale_f32_16x16x128_f8f6f4 v[64:67], v[84:87], v[64:67], 0, v233, v183 op_sel_hi:[0,0,0] cbsz:4 blgp:4
	v_mfma_scale_f32_16x16x128_f8f6f4 v[60:63], v[84:87], v[60:63], 0, v233, v183 op_sel_hi:[0,0,0] cbsz:4 blgp:4
	v_mfma_scale_f32_16x16x128_f8f6f4 v[56:59], v[84:87], v[56:59], 0, v233, v183 op_sel_hi:[0,0,0] cbsz:4 blgp:4
	v_mfma_scale_f32_16x16x128_f8f6f4 v[52:55], v[84:87], v[52:55], 0, v233, v183 op_sel_hi:[0,0,0] cbsz:4 blgp:4
	v_mfma_scale_f32_16x16x128_f8f6f4 v[48:51], v[84:87], v[48:51], 0, v233, v183 op_sel_hi:[0,0,0] cbsz:4 blgp:4
	v_mfma_scale_f32_16x16x128_f8f6f4 v[44:47], v[84:87], v[44:47], 0, v233, v183 op_sel_hi:[0,0,0] cbsz:4 blgp:4
	v_mfma_scale_f32_16x16x128_f8f6f4 v[36:39], v[84:87], v[36:39], 0, v233, v183 op_sel_hi:[0,0,0] cbsz:4 blgp:4
	v_mfma_scale_f32_16x16x128_f8f6f4 v[40:43], v[84:87], v[40:43], 0, v233, v183 op_sel_hi:[0,0,0] cbsz:4 blgp:4
	v_mfma_scale_f32_16x16x128_f8f6f4 v[32:35], v[84:87], v[32:35], 0, v233, v183 op_sel_hi:[0,0,0] cbsz:4 blgp:4
	v_mfma_scale_f32_16x16x128_f8f6f4 v[28:31], v[84:87], v[28:31], 0, v233, v183 op_sel_hi:[0,0,0] cbsz:4 blgp:4
	v_mfma_scale_f32_16x16x128_f8f6f4 v[24:27], v[84:87], v[24:27], 0, v233, v183 op_sel_hi:[0,0,0] cbsz:4 blgp:4
	v_mfma_scale_f32_16x16x128_f8f6f4 v[20:23], v[84:87], v[20:23], 0, v233, v183 op_sel_hi:[0,0,0] cbsz:4 blgp:4
	v_mfma_scale_f32_16x16x128_f8f6f4 v[16:19], v[84:87], v[16:19], 0, v233, v183 op_sel_hi:[0,0,0] cbsz:4 blgp:4
	v_mfma_scale_f32_16x16x128_f8f6f4 v[12:15], v[84:87], v[12:15], 0, v233, v183 op_sel_hi:[0,0,0] cbsz:4 blgp:4
	v_mfma_scale_f32_16x16x128_f8f6f4 v[8:11], v[84:87], v[8:11], 0, v233, v183 op_sel_hi:[0,0,0] cbsz:4 blgp:4
	s_nop 1
	v_add_f32_e32 v68, v68, v69
	v_add_f32_e32 v68, v68, v70
	v_add_f32_e32 v68, v68, v71
	v_add_f32_e32 v64, v64, v65
	v_add_f32_e32 v64, v64, v66
	v_add_f32_e32 v64, v64, v67
	v_add_f32_e32 v60, v60, v61
	v_add_f32_e32 v60, v60, v62
	v_add_f32_e32 v60, v60, v63
	v_add_f32_e32 v56, v56, v57
	v_add_f32_e32 v56, v56, v58
	v_add_f32_e32 v56, v56, v59
	v_add_f32_e32 v52, v52, v53
	v_add_f32_e32 v52, v52, v54
	v_add_f32_e32 v52, v52, v55
	v_add_f32_e32 v48, v48, v49
	v_add_f32_e32 v48, v48, v50
	v_add_f32_e32 v48, v48, v51
	v_add_f32_e32 v44, v44, v45
	v_add_f32_e32 v44, v44, v46
	v_add_f32_e32 v44, v44, v47
	v_add_f32_e32 v36, v36, v37
	v_add_f32_e32 v36, v36, v38
	v_add_f32_e32 v36, v36, v39
	v_add_f32_e32 v40, v40, v41
	v_add_f32_e32 v40, v40, v42
	v_add_f32_e32 v40, v40, v43
	v_add_f32_e32 v32, v32, v33
	v_add_f32_e32 v32, v32, v34
	v_add_f32_e32 v32, v32, v35
	v_add_f32_e32 v28, v28, v29
	v_add_f32_e32 v28, v28, v30
	v_add_f32_e32 v28, v28, v31
	v_add_f32_e32 v24, v24, v25
	v_add_f32_e32 v24, v24, v26
	v_add_f32_e32 v24, v24, v27
	v_add_f32_e32 v20, v20, v21
	v_add_f32_e32 v20, v20, v22
	v_add_f32_e32 v20, v20, v23
	v_add_f32_e32 v16, v16, v17
	v_add_f32_e32 v16, v16, v18
	v_add_f32_e32 v16, v16, v19
	v_add_f32_e32 v12, v12, v13
	v_add_f32_e32 v12, v12, v14
	v_add_f32_e32 v12, v12, v15
	v_add_f32_e32 v8, v8, v9
	v_add_f32_e32 v8, v8, v10
	v_add_f32_e32 v8, v8, v11
	ds_write2_b32 v122, v68, v64 offset1:16
	ds_write2_b32 v122, v60, v56 offset0:32 offset1:48
	ds_write2_b32 v122, v52, v48 offset0:64 offset1:80
	ds_write2_b32 v122, v44, v36 offset0:96 offset1:112
	ds_write2_b32 v122, v40, v32 offset0:128 offset1:144
	ds_write2_b32 v122, v28, v24 offset0:160 offset1:176
	ds_write2_b32 v122, v20, v16 offset0:192 offset1:208
	ds_write2_b32 v122, v12, v8 offset0:224 offset1:240
	s_branch .LBB0_1116
